# seam conversion stores made write-through (sc1) + DIL S tiles double-buffered + DIL V-load wait counted
# speedup vs baseline: 1.0144x; 1.0007x over previous
.Lmy_cvp0y_go:
	s_add_u32 s20, s50, s20
	s_addc_u32 s21, s51, 0
	v_and_b32_e32 v2, 7, v1
	v_lshrrev_b32_e32 v3, 3, v1
	s_lshl_b32 s24, s15, 6
	v_lshl_add_u32 v4, v2, 3, s24
	v_mul_lo_u32 v4, v4, s19
	v_lshl_add_u32 v5, v3, 2, s31
	v_add_u32_e32 v4, v4, v5
	v_mov_b32_e32 v5, 0
	v_lshlrev_b64 v[4:5], 2, v[4:5]
	s_lshl_b32 s26, s19, 2
	s_mov_b32 s27, 0
	s_lshr_b32 s28, s18, 8
	s_and_b32 s29, s18, 0xff
	s_lshl_b32 s28, s28, 5
	s_add_u32 s28, s28, s15
	s_lshl_b32 s28, s28, 8
	s_add_u32 s28, s28, s29
	s_waitcnt lgkmcnt(0)
	v_lshl_add_u64 v[4:5], s[12:13], 0, v[4:5]
	global_load_dwordx4 v[64:67], v[4:5], off nt
	v_lshl_add_u64 v[4:5], v[4:5], 0, s[26:27]
	global_load_dwordx4 v[68:71], v[4:5], off nt
	v_lshl_add_u64 v[4:5], v[4:5], 0, s[26:27]
	global_load_dwordx4 v[72:75], v[4:5], off nt
	v_lshl_add_u64 v[4:5], v[4:5], 0, s[26:27]
	global_load_dwordx4 v[76:79], v[4:5], off nt
	v_lshl_add_u64 v[4:5], v[4:5], 0, s[26:27]
	global_load_dwordx4 v[80:83], v[4:5], off nt
	v_lshl_add_u64 v[4:5], v[4:5], 0, s[26:27]
	global_load_dwordx4 v[84:87], v[4:5], off nt
	v_lshl_add_u64 v[4:5], v[4:5], 0, s[26:27]
	global_load_dwordx4 v[88:91], v[4:5], off nt
	v_lshl_add_u64 v[4:5], v[4:5], 0, s[26:27]
	global_load_dwordx4 v[92:95], v[4:5], off nt
	v_lshl_add_u32 v62, v3, 2, s28
	v_lshlrev_b32_e32 v62, 7, v62
	v_lshl_add_u32 v62, v2, 4, v62
	v_mov_b32_e32 v63, 0
	v_lshl_add_u64 v[62:63], s[20:21], 0, v[62:63]
	s_waitcnt vmcnt(8)
	v_cvt_pk_bf16_f32 v40, v8, v12
	v_cvt_pk_bf16_f32 v41, v16, v20
	v_cvt_pk_bf16_f32 v42, v24, v28
	v_cvt_pk_bf16_f32 v43, v32, v36
	global_store_dwordx4 v[6:7], v[40:43], off sc1
	v_cvt_pk_bf16_f32 v44, v9, v13
	v_cvt_pk_bf16_f32 v45, v17, v21
	v_cvt_pk_bf16_f32 v46, v25, v29
	v_cvt_pk_bf16_f32 v47, v33, v37
	global_store_dwordx4 v[6:7], v[44:47], off offset:128 sc1
	v_cvt_pk_bf16_f32 v48, v10, v14
	v_cvt_pk_bf16_f32 v49, v18, v22
	v_cvt_pk_bf16_f32 v50, v26, v30
	v_cvt_pk_bf16_f32 v51, v34, v38
	global_store_dwordx4 v[6:7], v[48:51], off offset:256 sc1
	v_cvt_pk_bf16_f32 v52, v11, v15
	v_cvt_pk_bf16_f32 v53, v19, v23
	v_cvt_pk_bf16_f32 v54, v27, v31
	v_cvt_pk_bf16_f32 v55, v35, v39
	global_store_dwordx4 v[6:7], v[52:55], off offset:384 sc1
	s_waitcnt vmcnt(4)
	v_cvt_pk_bf16_f32 v96, v64, v68
	v_cvt_pk_bf16_f32 v97, v72, v76
	v_cvt_pk_bf16_f32 v98, v80, v84
	v_cvt_pk_bf16_f32 v99, v88, v92
	global_store_dwordx4 v[62:63], v[96:99], off sc1
	v_cvt_pk_bf16_f32 v100, v65, v69
	v_cvt_pk_bf16_f32 v101, v73, v77
	v_cvt_pk_bf16_f32 v102, v81, v85
	v_cvt_pk_bf16_f32 v103, v89, v93
	global_store_dwordx4 v[62:63], v[100:103], off offset:128 sc1
	v_cvt_pk_bf16_f32 v104, v66, v70
	v_cvt_pk_bf16_f32 v105, v74, v78
	v_cvt_pk_bf16_f32 v106, v82, v86
	v_cvt_pk_bf16_f32 v107, v90, v94
	global_store_dwordx4 v[62:63], v[104:107], off offset:256 sc1
	v_cvt_pk_bf16_f32 v108, v67, v71
	v_cvt_pk_bf16_f32 v109, v75, v79
	v_cvt_pk_bf16_f32 v110, v83, v87
	v_cvt_pk_bf16_f32 v111, v91, v95
	global_store_dwordx4 v[62:63], v[108:111], off offset:384 sc1
	s_addk_i32 s34, 0x380
	s_cmpk_lt_u32 s34, 0x1200
	s_cbranch_scc1 .Lmy_p0x_loop
	s_branch .Lmy_p0x_done
.Lmy_p0x_single:
	s_waitcnt vmcnt(0)
	v_cvt_pk_bf16_f32 v40, v8, v12
	v_cvt_pk_bf16_f32 v41, v16, v20
	v_cvt_pk_bf16_f32 v42, v24, v28
	v_cvt_pk_bf16_f32 v43, v32, v36
	global_store_dwordx4 v[6:7], v[40:43], off sc1
	v_cvt_pk_bf16_f32 v44, v9, v13
	v_cvt_pk_bf16_f32 v45, v17, v21
	v_cvt_pk_bf16_f32 v46, v25, v29
	v_cvt_pk_bf16_f32 v47, v33, v37
	global_store_dwordx4 v[6:7], v[44:47], off offset:128 sc1
	v_cvt_pk_bf16_f32 v48, v10, v14
	v_cvt_pk_bf16_f32 v49, v18, v22
	v_cvt_pk_bf16_f32 v50, v26, v30
	v_cvt_pk_bf16_f32 v51, v34, v38
	global_store_dwordx4 v[6:7], v[48:51], off offset:256 sc1
	v_cvt_pk_bf16_f32 v52, v11, v15
	v_cvt_pk_bf16_f32 v53, v19, v23
	v_cvt_pk_bf16_f32 v54, v27, v31
	v_cvt_pk_bf16_f32 v55, v35, v39
	global_store_dwordx4 v[6:7], v[52:55], off offset:384 sc1

.Lmy_cv2_go:
	s_add_u32 s20, s50, s20
	s_addc_u32 s21, s51, 0
	v_and_b32_e32 v2, 7, v1
	v_lshrrev_b32_e32 v3, 3, v1
	s_lshl_b32 s24, s15, 6
	v_lshl_add_u32 v4, v2, 3, s24
	v_mul_lo_u32 v4, v4, s19
	v_lshl_add_u32 v5, v3, 2, s17
	v_add_u32_e32 v4, v4, v5
	v_mov_b32_e32 v5, 0
	v_lshlrev_b64 v[4:5], 2, v[4:5]
	s_lshl_b32 s26, s19, 2
	s_mov_b32 s27, 0
	s_lshr_b32 s28, s18, 8
	s_and_b32 s29, s18, 0xff
	s_lshl_b32 s28, s28, 5
	s_add_u32 s28, s28, s15
	s_lshl_b32 s28, s28, 8
	s_add_u32 s28, s28, s29
	s_waitcnt lgkmcnt(0)
	v_lshl_add_u64 v[4:5], s[12:13], 0, v[4:5]
	global_load_dwordx4 v[8:11], v[4:5], off nt
	v_lshl_add_u64 v[4:5], v[4:5], 0, s[26:27]
	global_load_dwordx4 v[12:15], v[4:5], off nt
	v_lshl_add_u64 v[4:5], v[4:5], 0, s[26:27]
	global_load_dwordx4 v[16:19], v[4:5], off nt
	v_lshl_add_u64 v[4:5], v[4:5], 0, s[26:27]
	global_load_dwordx4 v[20:23], v[4:5], off nt
	v_lshl_add_u64 v[4:5], v[4:5], 0, s[26:27]
	global_load_dwordx4 v[24:27], v[4:5], off nt
	v_lshl_add_u64 v[4:5], v[4:5], 0, s[26:27]
	global_load_dwordx4 v[28:31], v[4:5], off nt
	v_lshl_add_u64 v[4:5], v[4:5], 0, s[26:27]
	global_load_dwordx4 v[32:35], v[4:5], off nt
	v_lshl_add_u64 v[4:5], v[4:5], 0, s[26:27]
	global_load_dwordx4 v[36:39], v[4:5], off nt
	v_lshl_add_u32 v6, v3, 2, s28
	v_lshlrev_b32_e32 v6, 7, v6
	v_lshl_add_u32 v6, v2, 4, v6
	v_mov_b32_e32 v7, 0
	v_lshl_add_u64 v[6:7], s[20:21], 0, v[6:7]
	s_waitcnt vmcnt(0)
	v_cvt_pk_bf16_f32 v40, v8, v12
	v_cvt_pk_bf16_f32 v41, v16, v20
	v_cvt_pk_bf16_f32 v42, v24, v28
	v_cvt_pk_bf16_f32 v43, v32, v36
	global_store_dwordx4 v[6:7], v[40:43], off sc1
	v_cvt_pk_bf16_f32 v44, v9, v13
	v_cvt_pk_bf16_f32 v45, v17, v21
	v_cvt_pk_bf16_f32 v46, v25, v29
	v_cvt_pk_bf16_f32 v47, v33, v37
	global_store_dwordx4 v[6:7], v[44:47], off offset:128 sc1
	v_cvt_pk_bf16_f32 v48, v10, v14
	v_cvt_pk_bf16_f32 v49, v18, v22
	v_cvt_pk_bf16_f32 v50, v26, v30
	v_cvt_pk_bf16_f32 v51, v34, v38
	global_store_dwordx4 v[6:7], v[48:51], off offset:256 sc1
	v_cvt_pk_bf16_f32 v52, v11, v15
	v_cvt_pk_bf16_f32 v53, v19, v23
	v_cvt_pk_bf16_f32 v54, v27, v31
	v_cvt_pk_bf16_f32 v55, v35, v39
	global_store_dwordx4 v[6:7], v[52:55], off offset:384 sc1
	s_waitcnt vmcnt(0)

.LBB0_718:
	s_lshr_b32 s33, s97, 6
	s_lshl_b32 s78, s33, 4
	v_or_b32_e32 v82, s78, v171
	v_mad_u64_u32 v[252:253], s[30:31], v82, s86, v[154:155]
	v_or_b32_e32 v197, s78, v178
	ds_read_b128 v[210:213], v252
	ds_read_b128 v[214:217], v252 offset:64
	ds_read_b128 v[218:221], v252 offset:128
	ds_read_b128 v[222:225], v252 offset:192
	v_lshl_add_u32 v251, v197, 2, s71
	ds_read_b128 v[86:89], v251
	ds_read_b128 v[226:229], v252 offset:4352
	ds_read_b128 v[230:233], v252 offset:4416
	ds_read_b128 v[234:237], v252 offset:4480
	ds_read_b128 v[238:241], v252 offset:4544
	s_add_i32 s79, s78, 16
	s_add_i32 s42, s78, 32
	v_or_b32_e32 v199, s42, v178
	s_add_i32 s43, s78, 64
	v_or_b32_e32 v201, s43, v178
	s_add_i32 s30, s78, 0x60
	v_or_b32_e32 v203, s30, v178
	v_or_b32_e32 v198, s79, v178
	v_mov_b32_e32 v196, v192
	v_mov_b32_e32 v193, v163
	s_add_i32 s42, s78, 48
	v_or_b32_e32 v200, s42, v178
	s_add_i32 s43, s78, 0x50
	v_or_b32_e32 v202, s43, v178
	s_add_i32 s30, s78, 0x70
	s_add_i32 s31, s78, 0x80
	v_or_b32_e32 v204, s30, v178
	v_or_b32_e32 v205, s31, v178
	v_mov_b32_e32 v195, v191
	v_mov_b32_e32 v194, v190
	s_waitcnt lgkmcnt(4)
	v_mfma_f32_16x16x32_bf16 v[82:85], v[210:213], v[46:49], 0
	v_mfma_f32_16x16x32_bf16 v[82:85], v[214:217], v[42:45], v[82:85]
	v_mfma_f32_16x16x32_bf16 v[82:85], v[218:221], v[38:41], v[82:85]
	v_mfma_f32_16x16x32_bf16 v[82:85], v[222:225], v[34:37], v[82:85]
	ds_read_b128 v[210:213], v252 offset:8704
	ds_read_b128 v[214:217], v252 offset:8768
	ds_read_b128 v[218:221], v252 offset:8832
	ds_read_b128 v[222:225], v252 offset:8896
	s_waitcnt lgkmcnt(4)
	v_mfma_f32_16x16x32_bf16 v[90:93], v[226:229], v[46:49], 0
	v_mfma_f32_16x16x32_bf16 v[90:93], v[230:233], v[42:45], v[90:93]
	v_mfma_f32_16x16x32_bf16 v[90:93], v[234:237], v[38:41], v[90:93]
	v_mfma_f32_16x16x32_bf16 v[90:93], v[238:241], v[34:37], v[90:93]
	ds_read_b128 v[226:229], v252 offset:13056
	ds_read_b128 v[230:233], v252 offset:13120
	ds_read_b128 v[234:237], v252 offset:13184
	ds_read_b128 v[238:241], v252 offset:13248
	s_waitcnt lgkmcnt(4)
	v_mfma_f32_16x16x32_bf16 v[98:101], v[210:213], v[46:49], 0
	v_mfma_f32_16x16x32_bf16 v[98:101], v[214:217], v[42:45], v[98:101]
	v_mfma_f32_16x16x32_bf16 v[98:101], v[218:221], v[38:41], v[98:101]
	v_mfma_f32_16x16x32_bf16 v[98:101], v[222:225], v[34:37], v[98:101]
	ds_read_b128 v[210:213], v252 offset:17408
	ds_read_b128 v[214:217], v252 offset:17472
	ds_read_b128 v[218:221], v252 offset:17536
	ds_read_b128 v[222:225], v252 offset:17600
	s_waitcnt lgkmcnt(4)
	v_mfma_f32_16x16x32_bf16 v[106:109], v[226:229], v[46:49], 0
	v_mfma_f32_16x16x32_bf16 v[106:109], v[230:233], v[42:45], v[106:109]
	v_mfma_f32_16x16x32_bf16 v[106:109], v[234:237], v[38:41], v[106:109]
	v_mfma_f32_16x16x32_bf16 v[106:109], v[238:241], v[34:37], v[106:109]
	ds_read_b128 v[226:229], v252 offset:21760
	ds_read_b128 v[230:233], v252 offset:21824
	ds_read_b128 v[234:237], v252 offset:21888
	ds_read_b128 v[238:241], v252 offset:21952
	s_waitcnt lgkmcnt(4)
	v_mfma_f32_16x16x32_bf16 v[114:117], v[210:213], v[46:49], 0
	v_mfma_f32_16x16x32_bf16 v[114:117], v[214:217], v[42:45], v[114:117]
	v_mfma_f32_16x16x32_bf16 v[114:117], v[218:221], v[38:41], v[114:117]
	v_mfma_f32_16x16x32_bf16 v[114:117], v[222:225], v[34:37], v[114:117]
	ds_read_b128 v[210:213], v252 offset:26112
	ds_read_b128 v[214:217], v252 offset:26176
	ds_read_b128 v[218:221], v252 offset:26240
	ds_read_b128 v[222:225], v252 offset:26304
	s_waitcnt lgkmcnt(4)
	v_mfma_f32_16x16x32_bf16 v[122:125], v[226:229], v[46:49], 0
	v_mfma_f32_16x16x32_bf16 v[122:125], v[230:233], v[42:45], v[122:125]
	v_mfma_f32_16x16x32_bf16 v[122:125], v[234:237], v[38:41], v[122:125]
	v_mfma_f32_16x16x32_bf16 v[122:125], v[238:241], v[34:37], v[122:125]
	ds_read_b128 v[226:229], v252 offset:30464
	ds_read_b128 v[230:233], v252 offset:30528
	ds_read_b128 v[234:237], v252 offset:30592
	ds_read_b128 v[238:241], v252 offset:30656
	s_waitcnt lgkmcnt(4)
	v_mfma_f32_16x16x32_bf16 v[130:133], v[210:213], v[46:49], 0
	v_mfma_f32_16x16x32_bf16 v[130:133], v[214:217], v[42:45], v[130:133]
	v_mfma_f32_16x16x32_bf16 v[130:133], v[218:221], v[38:41], v[130:133]
	v_mfma_f32_16x16x32_bf16 v[130:133], v[222:225], v[34:37], v[130:133]
	ds_read_b128 v[210:213], v252 offset:34816
	ds_read_b128 v[214:217], v252 offset:34880
	ds_read_b128 v[218:221], v252 offset:34944
	ds_read_b128 v[222:225], v252 offset:35008
	s_waitcnt lgkmcnt(4)
	v_mfma_f32_16x16x32_bf16 v[138:141], v[226:229], v[46:49], 0
	v_mfma_f32_16x16x32_bf16 v[138:141], v[230:233], v[42:45], v[138:141]
	v_mfma_f32_16x16x32_bf16 v[138:141], v[234:237], v[38:41], v[138:141]
	v_mfma_f32_16x16x32_bf16 v[138:141], v[238:241], v[34:37], v[138:141]
	ds_read_b128 v[94:97], v251 offset:64
	ds_read_b128 v[102:105], v251 offset:128
	ds_read_b128 v[110:113], v251 offset:192
	ds_read_b128 v[118:121], v251 offset:256
	ds_read_b128 v[126:129], v251 offset:320
	ds_read_b128 v[134:137], v251 offset:384
	ds_read_b128 v[142:145], v251 offset:448
	ds_read_b128 v[150:153], v251 offset:512
	s_waitcnt lgkmcnt(8)
	v_mfma_f32_16x16x32_bf16 v[146:149], v[210:213], v[46:49], 0
	v_mfma_f32_16x16x32_bf16 v[146:149], v[214:217], v[42:45], v[146:149]
	v_mfma_f32_16x16x32_bf16 v[146:149], v[218:221], v[38:41], v[146:149]
	v_mfma_f32_16x16x32_bf16 v[146:149], v[222:225], v[34:37], v[146:149]
	s_and_b64 vcc, exec, s[26:27]
	s_cbranch_vccnz .LBB0_724
	s_andn2_b64 vcc, exec, s[76:77]
	s_mov_b64 s[26:27], -1
	s_cbranch_vccnz .LBB0_721
	s_lshl_b32 s31, s95, 6
	s_mov_b64 s[26:27], 0
